# grid barriers 2..10: one L2 write-back per XCD (XCC census at seam 1, per-XCC arrival counter, XCC leader flushes then arrives on top counter)
# speedup vs baseline: 1.0098x; 1.0098x over previous
; #define LAS __attribute__((address_space(3)))
; __global__ void __launch_bounds__(512) fwd_mega(Args a) {
;     extern __shared__ __attribute__((aligned(16))) unsigned char lds_raw[];
;     LAS unsigned char* lds = (LAS unsigned char*)lds_raw;
;     cg::grid_group grid = cg::this_grid();
;     const int tid = threadIdx.x, lane = tid & 63, wave = __builtin_amdgcn_readfirstlane(tid >> 6);
;     const int G = gridDim.x, bx = blockIdx.x;
;     const int vcu = (G % 8 == 0) ? (bx % 8) * (G / 8) + bx / 8 : bx;
;     unsigned char* ws = a.ws;
_Z8fwd_mega4Args:
	s_load_dwordx16 s[72:87], s[0:1], 0x0
	s_load_dwordx8 s[24:31], s[0:1], 0x80
	s_load_dwordx4 s[52:55], s[0:1], 0xa0
	s_load_dword s3, s[0:1], 0xb0
	s_add_u32 s58, s0, 0xb0
	s_mov_b32 s60, s2
	s_addc_u32 s59, s1, 0
	v_and_b32_e32 v162, 0x3ff, v0
	s_waitcnt lgkmcnt(0)
	s_cmp_eq_u32 s60, 0
	s_cbranch_scc0 .Lsm_init_done
	v_and_b32_e32 v254, 31, v162
	v_lshlrev_b32_e32 v254, 8, v254
	v_add_u32_e32 v254, 0x400, v254
	v_mov_b32_e32 v255, 0
	global_store_dword v254, v255, s[52:53]

.LBB0_170:
	s_cmp_gt_i32 s55, 2
	s_cselect_b64 s[0:1], -1, 0
	s_and_b64 s[4:5], s[20:21], s[0:1]
	s_andn2_b64 vcc, exec, s[4:5]
	s_cbranch_vccnz .LBB0_186
	v_readlane_b32 s8, v253, 42
	v_readlane_b32 s9, v253, 43
	s_waitcnt vmcnt(0) lgkmcnt(0)
	s_barrier
	v_readfirstlane_b32 s98, v162
	s_nop 3
	s_cmp_lt_u32 s98, 64
	s_cbranch_scc0 .Lsm1_wait
	buffer_wbl2 sc1
	s_waitcnt vmcnt(0)
	s_getreg_b32 s98, hwreg(20, 0, 4)
	v_writelane_b32 v253, s98, 60
	s_mov_b64 vcc, exec
	s_mov_b64 exec, 1
	s_lshl_b32 s99, s98, 8
	s_add_u32 s99, s99, 0x1000
	v_mov_b32_e32 v254, s99
	v_mov_b32_e32 v255, 1
	global_atomic_add v255, v254, v255, s[52:53] sc0
	s_waitcnt vmcnt(0)
	v_readfirstlane_b32 s100, v255
	s_nop 3
	s_cmp_eq_u32 s100, 0
	s_cselect_b32 s100, 1, 0
	v_writelane_b32 v253, s100, 63
	s_and_b32 s99, s60, 7
	s_lshl_b32 s99, s99, 8
	s_add_u32 s99, s99, 0x400
	v_mov_b32_e32 v254, s99
	v_mov_b32_e32 v255, 1
	global_atomic_add v254, v255, s[52:53]
	s_mov_b64 exec, 0xff
	s_lshr_b32 s99, s56, 3
	v_mbcnt_lo_u32_b32 v254, -1, 0
	v_lshlrev_b32_e32 v254, 8, v254
	v_add_u32_e32 v254, 0x400, v254
	s_mov_b32 s100, 0

.Lsm1_pd:
	v_mbcnt_lo_u32_b32 v254, -1, 0
	v_lshlrev_b32_e32 v254, 8, v254
	v_add_u32_e32 v254, 0x1000, v254
	global_load_dword v255, v254, s[52:53] sc1
	s_waitcnt vmcnt(0)
	v_readlane_b32 s98, v253, 60
	s_nop 3
	v_readlane_b32 s99, v255, s98
	s_nop 3
	v_writelane_b32 v253, s99, 61
	v_cmp_ne_u32_e64 s[100:101], 0, v255
	s_nop 1
	s_bcnt1_i32_b64 s100, s[100:101]
	v_writelane_b32 v253, s100, 62
	s_mov_b64 exec, vcc
	buffer_inv sc1
	s_waitcnt vmcnt(0)

.LBB0_285:
	s_cmp_gt_i32 s55, 3
	s_cselect_b64 s[0:1], -1, 0
	s_and_b64 s[4:5], s[12:13], s[0:1]
	v_readlane_b32 s92, v253, 42
	s_andn2_b64 vcc, exec, s[4:5]
	v_readlane_b32 s93, v253, 43
	s_cbranch_vccnz .LBB0_301
	v_readlane_b32 s6, v253, 48
	s_waitcnt vmcnt(0) lgkmcnt(0)
	s_barrier
	v_readfirstlane_b32 s98, v162
	s_nop 3
	s_cmp_lt_u32 s98, 64
	s_cbranch_scc0 .Lsm2_wait
	s_mov_b64 vcc, exec
	s_mov_b64 exec, 1
	v_readlane_b32 s98, v253, 60
	v_readlane_b32 s99, v253, 63
	s_nop 3
	s_lshl_b32 s100, s98, 8
	s_add_u32 s100, s100, 0x1800
	v_mov_b32_e32 v254, s100
	v_mov_b32_e32 v255, 1
	global_atomic_add v254, v255, s[52:53]
	s_cmp_eq_u32 s99, 0
	s_cbranch_scc1 .Lsm2_nl
	v_readlane_b32 s99, v253, 61
	s_nop 3
	s_mul_i32 s99, s99, 1
	s_mov_b32 s100, 0
.Lsm2_x:
	global_load_dword v255, v254, s[52:53] sc1
	s_waitcnt vmcnt(0)
	v_readlane_b32 s98, v255, 0
	s_nop 3
	s_cmp_ge_u32 s98, s99
	s_cbranch_scc1 .Lsm2_xd
	s_add_u32 s100, s100, 1
	s_cmp_lt_u32 s100, 0x4000
	s_cbranch_scc0 .Lsm2_xd
	s_sleep 1
	s_branch .Lsm2_x
.Lsm2_xd:
	buffer_wbl2 sc1
	s_waitcnt vmcnt(0)
	v_mov_b32_e32 v254, 0x2000
	v_mov_b32_e32 v255, 1
	global_atomic_add v254, v255, s[52:53]
.Lsm2_nl:
	v_readlane_b32 s99, v253, 62
	s_nop 3
	s_mul_i32 s99, s99, 1
	v_mov_b32_e32 v254, 0x2000
	s_mov_b32 s100, 0

.LBB0_682:
	s_cmp_gt_i32 s55, 4
	s_cselect_b64 s[0:1], -1, 0
	s_and_b64 s[4:5], s[44:45], s[0:1]
	v_readlane_b32 s76, v253, 26
	s_andn2_b64 vcc, exec, s[4:5]
	v_readlane_b32 s77, v253, 27
	v_readlane_b32 s80, v253, 30
	v_readlane_b32 s81, v253, 31
	v_readlane_b32 s82, v253, 32
	v_readlane_b32 s83, v253, 33
	v_readlane_b32 s84, v253, 34
	v_readlane_b32 s85, v253, 35
	v_readlane_b32 s94, v253, 48
	v_readlane_b32 s78, v253, 28
	v_readlane_b32 s79, v253, 29
	v_readlane_b32 s86, v253, 36
	v_readlane_b32 s87, v253, 37
	v_readlane_b32 s88, v253, 38
	v_readlane_b32 s89, v253, 39
	v_readlane_b32 s90, v253, 40
	v_readlane_b32 s91, v253, 41
	s_cbranch_vccnz .LBB0_698
	s_waitcnt vmcnt(0) lgkmcnt(0)
	s_barrier
	v_readfirstlane_b32 s98, v162
	s_nop 3
	s_cmp_lt_u32 s98, 64
	s_cbranch_scc0 .Lsm3_wait
	s_mov_b64 vcc, exec
	s_mov_b64 exec, 1
	v_readlane_b32 s98, v253, 60
	v_readlane_b32 s99, v253, 63
	s_nop 3
	s_lshl_b32 s100, s98, 8
	s_add_u32 s100, s100, 0x1800
	v_mov_b32_e32 v254, s100
	v_mov_b32_e32 v255, 1
	global_atomic_add v254, v255, s[52:53]
	s_cmp_eq_u32 s99, 0
	s_cbranch_scc1 .Lsm3_nl
	v_readlane_b32 s99, v253, 61
	s_nop 3
	s_mul_i32 s99, s99, 2
	s_mov_b32 s100, 0

.Lsm3_nl:
	v_readlane_b32 s99, v253, 62
	s_nop 3
	s_mul_i32 s99, s99, 2
	v_mov_b32_e32 v254, 0x2000
	s_mov_b32 s100, 0

.LBB0_723:
	s_cmp_gt_i32 s55, 5
	s_cselect_b64 s[0:1], -1, 0
	s_and_b64 s[4:5], s[4:5], s[0:1]
	s_andn2_b64 vcc, exec, s[4:5]
	s_cbranch_vccnz .LBB0_739
	s_waitcnt vmcnt(0) lgkmcnt(0)
	s_barrier
	v_readfirstlane_b32 s98, v162
	s_nop 3
	s_cmp_lt_u32 s98, 64
	s_cbranch_scc0 .Lsm4_wait
	s_mov_b64 vcc, exec
	s_mov_b64 exec, 1
	v_readlane_b32 s98, v253, 60
	v_readlane_b32 s99, v253, 63
	s_nop 3
	s_lshl_b32 s100, s98, 8
	s_add_u32 s100, s100, 0x1800
	v_mov_b32_e32 v254, s100
	v_mov_b32_e32 v255, 1
	global_atomic_add v254, v255, s[52:53]
	s_cmp_eq_u32 s99, 0
	s_cbranch_scc1 .Lsm4_nl
	v_readlane_b32 s99, v253, 61
	s_nop 3
	s_mul_i32 s99, s99, 3
	s_mov_b32 s100, 0

.Lsm4_nl:
	v_readlane_b32 s99, v253, 62
	s_nop 3
	s_mul_i32 s99, s99, 3
	v_mov_b32_e32 v254, 0x2000
	s_mov_b32 s100, 0

.LBB0_788:
	s_cmp_gt_i32 s55, 6
	s_cselect_b64 s[0:1], -1, 0
	s_and_b64 s[4:5], s[4:5], s[0:1]
	s_andn2_b64 vcc, exec, s[4:5]
	s_cbranch_vccnz .LBB0_804
	s_waitcnt vmcnt(0) lgkmcnt(0)
	s_barrier
	v_readfirstlane_b32 s98, v162
	s_nop 3
	s_cmp_lt_u32 s98, 64
	s_cbranch_scc0 .Lsm5_wait
	s_mov_b64 vcc, exec
	s_mov_b64 exec, 1
	v_readlane_b32 s98, v253, 60
	v_readlane_b32 s99, v253, 63
	s_nop 3
	s_lshl_b32 s100, s98, 8
	s_add_u32 s100, s100, 0x1800
	v_mov_b32_e32 v254, s100
	v_mov_b32_e32 v255, 1
	global_atomic_add v254, v255, s[52:53]
	s_cmp_eq_u32 s99, 0
	s_cbranch_scc1 .Lsm5_nl
	v_readlane_b32 s99, v253, 61
	s_nop 3
	s_mul_i32 s99, s99, 4
	s_mov_b32 s100, 0

.Lsm5_nl:
	v_readlane_b32 s99, v253, 62
	s_nop 3
	s_mul_i32 s99, s99, 4
	v_mov_b32_e32 v254, 0x2000
	s_mov_b32 s100, 0

.LBB0_863:
	s_cmp_gt_i32 s55, 7
	s_cselect_b64 s[0:1], -1, 0
	s_and_b64 s[4:5], s[18:19], s[0:1]
	s_andn2_b64 vcc, exec, s[4:5]
	s_cbranch_vccnz .LBB0_879
	s_waitcnt vmcnt(0) lgkmcnt(0)
	s_barrier
	v_readfirstlane_b32 s98, v162
	s_nop 3
	s_cmp_lt_u32 s98, 64
	s_cbranch_scc0 .Lsm6_wait
	s_mov_b64 vcc, exec
	s_mov_b64 exec, 1
	v_readlane_b32 s98, v253, 60
	v_readlane_b32 s99, v253, 63
	s_nop 3
	s_lshl_b32 s100, s98, 8
	s_add_u32 s100, s100, 0x1800
	v_mov_b32_e32 v254, s100
	v_mov_b32_e32 v255, 1
	global_atomic_add v254, v255, s[52:53]
	s_cmp_eq_u32 s99, 0
	s_cbranch_scc1 .Lsm6_nl
	v_readlane_b32 s99, v253, 61
	s_nop 3
	s_mul_i32 s99, s99, 5
	s_mov_b32 s100, 0

.Lsm6_nl:
	v_readlane_b32 s99, v253, 62
	s_nop 3
	s_mul_i32 s99, s99, 5
	v_mov_b32_e32 v254, 0x2000
	s_mov_b32 s100, 0

.LBB0_882:
	s_cmp_gt_i32 s55, 8
	s_cselect_b64 s[0:1], -1, 0
	s_and_b64 s[4:5], s[4:5], s[0:1]
	v_readlane_b32 s68, v253, 24
	s_andn2_b64 vcc, exec, s[4:5]
	v_readlane_b32 s69, v253, 25
	s_cbranch_vccnz .LBB0_898
	s_waitcnt vmcnt(0) lgkmcnt(0)
	s_barrier
	v_readfirstlane_b32 s98, v162
	s_nop 3
	s_cmp_lt_u32 s98, 64
	s_cbranch_scc0 .Lsm7_wait
	s_mov_b64 vcc, exec
	s_mov_b64 exec, 1
	v_readlane_b32 s98, v253, 60
	v_readlane_b32 s99, v253, 63
	s_nop 3
	s_lshl_b32 s100, s98, 8
	s_add_u32 s100, s100, 0x1800
	v_mov_b32_e32 v254, s100
	v_mov_b32_e32 v255, 1
	global_atomic_add v254, v255, s[52:53]
	s_cmp_eq_u32 s99, 0
	s_cbranch_scc1 .Lsm7_nl
	v_readlane_b32 s99, v253, 61
	s_nop 3
	s_mul_i32 s99, s99, 6
	s_mov_b32 s100, 0

.Lsm7_nl:
	v_readlane_b32 s99, v253, 62
	s_nop 3
	s_mul_i32 s99, s99, 6
	v_mov_b32_e32 v254, 0x2000
	s_mov_b32 s100, 0

.LBB0_927:
	s_cmp_gt_i32 s55, 9
	s_cselect_b64 s[0:1], -1, 0
	s_and_b64 s[4:5], s[22:23], s[0:1]
	s_andn2_b64 vcc, exec, s[4:5]
	s_cbranch_vccnz .LBB0_943
	s_waitcnt vmcnt(0) lgkmcnt(0)
	s_barrier
	v_readfirstlane_b32 s98, v162
	s_nop 3
	s_cmp_lt_u32 s98, 64
	s_cbranch_scc0 .Lsm8_wait
	s_mov_b64 vcc, exec
	s_mov_b64 exec, 1
	v_readlane_b32 s98, v253, 60
	v_readlane_b32 s99, v253, 63
	s_nop 3
	s_lshl_b32 s100, s98, 8
	s_add_u32 s100, s100, 0x1800
	v_mov_b32_e32 v254, s100
	v_mov_b32_e32 v255, 1
	global_atomic_add v254, v255, s[52:53]
	s_cmp_eq_u32 s99, 0
	s_cbranch_scc1 .Lsm8_nl
	v_readlane_b32 s99, v253, 61
	s_nop 3
	s_mul_i32 s99, s99, 7
	s_mov_b32 s100, 0

.Lsm8_nl:
	v_readlane_b32 s99, v253, 62
	s_nop 3
	s_mul_i32 s99, s99, 7
	v_mov_b32_e32 v254, 0x2000
	s_mov_b32 s100, 0

.LBB0_954:
	s_cmp_gt_i32 s55, 10
	s_cselect_b64 s[0:1], -1, 0
	s_and_b64 s[4:5], s[4:5], s[0:1]
	s_andn2_b64 vcc, exec, s[4:5]
	s_cbranch_vccnz .LBB0_970
	s_waitcnt vmcnt(0) lgkmcnt(0)
	s_barrier
	v_readfirstlane_b32 s98, v162
	s_nop 3
	s_cmp_lt_u32 s98, 64
	s_cbranch_scc0 .Lsm9_wait
	s_mov_b64 vcc, exec
	s_mov_b64 exec, 1
	v_readlane_b32 s98, v253, 60
	v_readlane_b32 s99, v253, 63
	s_nop 3
	s_lshl_b32 s100, s98, 8
	s_add_u32 s100, s100, 0x1800
	v_mov_b32_e32 v254, s100
	v_mov_b32_e32 v255, 1
	global_atomic_add v254, v255, s[52:53]
	s_cmp_eq_u32 s99, 0
	s_cbranch_scc1 .Lsm9_nl
	v_readlane_b32 s99, v253, 61
	s_nop 3
	s_mul_i32 s99, s99, 8
	s_mov_b32 s100, 0

.Lsm9_nl:
	v_readlane_b32 s99, v253, 62
	s_nop 3
	s_mul_i32 s99, s99, 8
	v_mov_b32_e32 v254, 0x2000
	s_mov_b32 s100, 0

.LBB0_1033:
	s_cmp_gt_i32 s55, 11
	s_cselect_b64 s[0:1], -1, 0
	s_and_b64 s[2:3], s[8:9], s[0:1]
	s_andn2_b64 vcc, exec, s[2:3]
	s_cbranch_vccnz .LBB0_1049
	s_waitcnt vmcnt(0) lgkmcnt(0)
	s_barrier
	v_readfirstlane_b32 s98, v162
	s_nop 3
	s_cmp_lt_u32 s98, 64
	s_cbranch_scc0 .Lsm10_wait
	s_mov_b64 vcc, exec
	s_mov_b64 exec, 1
	v_readlane_b32 s98, v253, 60
	v_readlane_b32 s99, v253, 63
	s_nop 3
	s_lshl_b32 s100, s98, 8
	s_add_u32 s100, s100, 0x1800
	v_mov_b32_e32 v254, s100
	v_mov_b32_e32 v255, 1
	global_atomic_add v254, v255, s[52:53]
	s_cmp_eq_u32 s99, 0
	s_cbranch_scc1 .Lsm10_nl
	v_readlane_b32 s99, v253, 61
	s_nop 3
	s_mul_i32 s99, s99, 9
	s_mov_b32 s100, 0

.Lsm10_nl:
	v_readlane_b32 s99, v253, 62
	s_nop 3
	s_mul_i32 s99, s99, 9
	v_mov_b32_e32 v254, 0x2000
	s_mov_b32 s100, 0
